# static s_setprio 1 for waves 4-7 for the duration of the differential-attention phase (reset to 0 at its end)
# baseline (speedup 1.0000x reference)
.LBB0_417:
	s_and_b64 vcc, exec, s[6:7]
	s_cbranch_vccz .LBB0_700
	s_cmp_gt_i32 s34, 1
	s_mov_b64 s[6:7], -1
	s_cbranch_scc0 .LBB0_579
	v_mov_b32_e32 v224, v234
	v_writelane_b32 v255, s34, 32
	s_mov_b32 s44, 0
	v_readfirstlane_b32 s0, v224
	s_nop 1
	v_writelane_b32 v255, s0, 33
	s_cmp_ge_u32 s0, 0x100
	s_cbranch_scc0 .Lattn_prio_done
	s_setprio 1
.Lattn_prio_done:
	s_add_u32 s0, s78, 0xaa00000
	s_addc_u32 s1, s79, 0
	s_add_u32 s20, s78, 0xba00000
	s_addc_u32 s21, s79, 0
	s_add_u32 s22, s78, 0xca00000
	s_addc_u32 s23, s79, 0
	s_add_u32 s26, s78, 0x8a00000
	s_addc_u32 s27, s79, 0
	s_ashr_i32 s5, s59, 31
	s_ashr_i32 s96, s81, 31
	s_lshr_b32 s5, s5, 29
	s_lshr_b32 s4, s96, 29
	s_add_i32 s5, s59, s5
	s_add_i32 s4, s81, s4
	s_and_b32 s6, s5, -8
	s_ashr_i32 s4, s4, 3
	s_sub_i32 s6, s59, s6
	s_mul_i32 s4, s6, s4
	s_ashr_i32 s5, s5, 3
	s_add_i32 s4, s4, s5
	s_and_b32 s34, s4, 7
	s_ashr_i32 s35, s4, 3
	s_xor_b32 s37, s34, 15
	s_or_b32 s38, s34, 16
	s_xor_b32 s39, s34, 31
	s_branch .LBB0_422

.LBB0_507:
	s_setprio 0
	v_readlane_b32 s9, v255, 24
	s_cmpk_lt_i32 s9, 0xc0
	s_mul_hi_i32 s4, s9, 0x55555556
	s_cselect_b64 s[0:1], -1, 0
	s_lshr_b32 s5, s4, 31
	s_add_i32 s6, s4, s5
	s_mul_i32 s4, s6, 3
	s_sub_i32 s7, s9, s4
	s_cmp_eq_u32 s7, 2
	s_cselect_b64 s[4:5], -1, 0
	s_lshl_b32 s8, s6, 1
	s_add_i32 s8, s8, s7
	s_addk_i32 s6, 0x280
	s_add_i32 s7, s9, 0xc0
	s_and_b64 s[38:39], s[0:1], s[4:5]
	s_and_b64 s[0:1], s[38:39], exec
	s_cselect_b32 s4, s6, s8
	s_cmpk_lt_i32 s9, 0xc0
	s_cselect_b64 s[44:45], -1, 0
	s_and_b64 s[0:1], s[44:45], exec
	s_cselect_b32 s0, s4, s7
	s_add_u32 s46, s78, 0x10a00000
	s_addc_u32 s47, s79, 0
	s_add_u32 s60, s78, 0x13a00000
	s_mul_hi_i32 s1, s0, 0x2aaaaaab
	s_addc_u32 s61, s79, 0
	s_lshr_b32 s4, s1, 31
	s_ashr_i32 s1, s1, 6
	s_add_i32 s1, s1, s4
	s_mul_i32 s4, s1, 0x180
	s_sub_i32 s4, s0, s4
	s_ashr_i32 s5, s4, 7
	s_lshl_b32 s9, s5, 1
	s_mulk_i32 s1, 0x300
	s_lshl_b32 s5, s5, 8
	s_and_b32 s8, s4, 31
	s_add_i32 s5, s5, s1
	s_lshl_b32 s1, s4, 1
	s_and_b32 s1, s1, 0xc0
	s_lshr_b32 s4, s8, s9
	s_or_b32 s1, s5, s1
	s_lshl_b32 s4, s4, 1
	s_lshl_b32 s5, -1, s9
	s_lshl_b32 s4, s4, s9
	s_andn2_b32 s5, s8, s5
	s_or_b32 s4, s4, s5
	s_add_i32 s1, s1, s4
	s_mul_hi_i32 s4, s1, 0x2aaaaaab
	s_lshr_b32 s5, s4, 31
	s_ashr_i32 s4, s4, 7
	s_add_i32 s4, s4, s5
	s_mul_i32 s5, s4, 0x300
	s_sub_i32 s1, s1, s5
	s_ashr_i32 s8, s1, 8
	s_lshl_b32 s35, s8, 1
	s_and_b32 s5, s1, 63
	s_lshl_b32 s9, -1, s35
	s_andn2_b32 s36, s5, s9
	s_lshr_b32 s9, s5, s35
	s_ashr_i32 s5, s4, 31
	s_lshl_b32 s1, s1, 1
	s_lshl_b64 s[22:23], s[4:5], 13
	s_lshl_b32 s4, s8, 9
	s_and_b32 s1, s1, 0x180
	s_or_b32 s4, s4, s1
	v_lshlrev_b32_e32 v1, 3, v224
	v_ashrrev_i32_e32 v135, 4, v224
	s_cmp_lg_u32 s9, 0
	v_mov_b32_e32 v2, v0
	v_mov_b32_e32 v3, v0
	v_mov_b32_e32 v6, v0
	s_waitcnt lgkmcnt(0)
	v_mov_b32_e32 v7, v0
	v_and_b32_e32 v133, 0x78, v1
	v_cmp_lt_i32_e64 s[6:7], s25, v135
	s_cselect_b64 s[26:27], -1, 0
	s_lshl_b32 s37, s9, 7
	s_ashr_i32 s5, s4, 31
	v_mov_b32_e32 v1, v0
	v_mov_b32_e32 v4, v0
	v_mov_b32_e32 v5, v0
	v_mov_b64_e32 v[10:11], v[6:7]
	v_mov_b64_e32 v[14:15], v[2:3]
	v_readfirstlane_b32 s34, v224
	s_add_i32 s1, s37, 0xffffff80
	v_or_b32_e32 v68, s4, v133
	v_mov_b32_e32 v69, s5
	s_or_b64 s[10:11], s[6:7], s[26:27]
	v_mov_b64_e32 v[8:9], v[4:5]
	v_mov_b64_e32 v[12:13], v[0:1]
	s_barrier
	s_and_saveexec_b64 s[8:9], s[10:11]
	s_cbranch_execz .LBB0_509
	v_add_u32_e32 v1, s1, v135
	v_lshlrev_b32_e32 v1, s35, v1
	v_add_u32_e32 v2, s36, v1
	v_ashrrev_i32_e32 v3, 31, v2
	v_lshl_add_u64 v[2:3], s[22:23], 0, v[2:3]
	s_movk_i32 s12, 0x600
	v_mad_u64_u32 v[8:9], s[10:11], v2, s12, v[68:69]
	v_mad_i32_i24 v9, v3, s12, v9
	v_lshlrev_b64 v[2:3], 1, v[8:9]
	v_lshl_add_u64 v[8:9], s[60:61], 0, v[2:3]
	v_lshl_add_u64 v[2:3], s[46:47], 0, v[2:3]
	global_load_dwordx4 v[8:11], v[8:9], off
	s_nop 0
	global_load_dwordx4 v[12:15], v[2:3], off
